# c17: dense attention stages 128 keys per LDS stage (two 64-key sub-tiles), one block barrier per 128 keys instead of per 64
# baseline (speedup 1.0000x reference)
; #define ATA_LOAD(RK, RV, t) do { const size_t tb = (size_t)(t) * 64 * 128; RK[0] = *(const u32x4*)(Kb + tb + goff0); RV[0] = *(const u32x4*)(Vb + tb + goff0); } while (0)
; #define ATA_STORE(RK, RV, st) do { unsigned char* sb_ = smem + (st) * ATA_STAGE; *(u32x4*)(sb_ + ko0) = RK[0]; *(u32x4*)(sb_ + vo0) = RV[0]; } while (0)
; __device__ void attn_a_item(const Params& p, int item, int l, unsigned char* smem) {
;     int tid_ = threadIdx.x; asm volatile("" : "+v"(tid_));
;     const int tid = tid_, lane = tid & 63, w = __builtin_amdgcn_readfirstlane(tid >> 6), r32 = lane & 31, hi = lane >> 5;
;     const int b = item >> 8, r = item & 255, kvh = r >> 7, qblk = (r >> 2) & 31, hq = kvh * 4 + (r & 3);
;     float* lq = (float*)(smem + ATA_LQ) + w * 32;
;     bf16_t* QA = (bf16_t*)(p.ws + WS_QA);
;     const bf16_t* GA = (const bf16_t*)(p.ws + WS_GA);
;     const size_t tokq = (size_t)b * SEQ + qblk * 256 + w * 32;
;     bf16x8 qr[4];
; #pragma unroll
;     for (int ds = 0; ds < 4; ++ds) qr[ds] = *(const bf16x8*)(QA + (tokq + r32) * 512 + hq * 64 + ds * 16 + hi * 8);
;     const bf16_t* Kb = (const bf16_t*)(p.ws + WS_KA) + (size_t)b * SEQ * 128 + kvh * 64;
;     const bf16_t* Vb = (const bf16_t*)(p.ws + WS_VA) + (size_t)b * SEQ * 128 + kvh * 64;
;     const float nshift = -((const float*)(p.ws + WS_BND))[l];
;     f32x16 o0, o1;
; #pragma unroll
;     for (int i = 0; i < 16; ++i) { o0[i] = 0.f; o1[i] = 0.f; }
;     f32x4 la4 = (f32x4){0.f, 0.f, 0.f, 0.f};
;     constexpr int NT = SEQ / 64;
;     const int row0 = tid >> 3, ch0 = tid & 7;
;     const size_t goff0 = (size_t)row0 * 128 + ch0 * 8;
;     const int ko0 = row0 * 144 + ch0 * 16;
;     const int vo0 = 9216 + (ch0 >> 2) * 4096 + row0 * 64 + (ch0 & 3) * 16;
;     u32x4 rkA[1], rvA[1], rkB[1], rvB[1];
;     ...
;     __syncthreads();
;     ATA_LOAD(rkA, rvA, 0); ATA_LOAD(rkB, rvB, 1);
;     ATA_STORE(rkA, rvA, 0);
;     ATA_LOAD(rkA, rvA, 2);
;     __syncthreads();
.LBB0_845:
	v_mov_b32_e32 v11, v210
	s_ashr_i32 s20, s49, 8
	v_readfirstlane_b32 s9, v11
	s_ashr_i32 s17, s9, 1
	s_ashr_i32 s21, s20, 31
	s_lshl_b32 s22, s49, 6
	s_bfe_u32 s12, s49, 0x10007
	s_andn2_b32 s17, s17, 31
	s_lshl_b64 s[18:19], s[20:21], 13
	s_and_b32 s9, s22, 0x1f00
	s_lshl_b32 s24, s12, 7
	s_ashr_i32 s16, s17, 31
	s_or_b32 s9, s18, s9
	s_add_u32 s9, s9, s17
	v_and_b32_e32 v153, 31, v11
	s_addc_u32 s16, s19, s16
	v_or_b32_e32 v0, s9, v153
	v_mov_b32_e32 v1, s16
	s_lshl_b32 s12, s12, 8
	s_and_b32 s18, s22, 0xc0
	v_lshlrev_b64 v[0:1], 10, v[0:1]
	s_or_b32 s18, s12, s18
	v_lshl_add_u64 v[0:1], s[36:37], 0, v[0:1]
	s_lshl_b32 s12, s18, 1
	s_lshl_b64 s[44:45], s[20:21], 21
	v_lshl_add_u64 v[0:1], v[0:1], 0, s[12:13]
	s_add_u32 s12, s11, s44
	s_addc_u32 s19, s46, s45
	v_bfe_u32 v152, v11, 5, 1
	s_add_u32 s20, s47, s44
	v_ashrrev_i32_e32 v8, 3, v11
	v_lshlrev_b32_e32 v80, 4, v152
	s_addc_u32 s21, s48, s45
	v_ashrrev_i32_e32 v9, 31, v8
	v_lshlrev_b32_e32 v23, 4, v11
	v_lshl_add_u64 v[0:1], v[0:1], 0, v[80:81]
	s_add_u32 s20, s20, s24
	v_and_b32_e32 v10, 0x70, v23
	v_lshlrev_b64 v[12:13], 8, v[8:9]
	global_load_dwordx4 v[82:85], v[0:1], off
	global_load_dwordx4 v[86:89], v[0:1], off offset:32
	global_load_dwordx4 v[90:93], v[0:1], off offset:64
	global_load_dwordx4 v[94:97], v[0:1], off offset:96
	s_addc_u32 s21, s21, 0
	v_or_b32_e32 v0, v12, v10
	v_mov_b32_e32 v1, v13
	v_lshl_add_u64 v[14:15], s[20:21], 0, v[0:1]
	s_add_u32 s22, s12, s24
	v_add_co_u32_e32 v18, vcc, s34, v14
	s_addc_u32 s23, s19, 0
	s_nop 0
	v_addc_co_u32_e32 v19, vcc, 0, v15, vcc
	s_mov_b32 s19, 0x8000
	global_load_dword v22, v81, s[38:39]
	s_barrier
	v_lshl_add_u64 v[16:17], s[22:23], 0, v[0:1]
	global_load_dwordx4 v[0:3], v[14:15], off
	global_load_dwordx4 v[4:7], v[16:17], off
	v_add_co_u32_e32 v14, vcc, s19, v14
	v_lshlrev_b32_e32 v9, 10, v11
	s_nop 0
	v_addc_co_u32_e32 v15, vcc, 0, v15, vcc
	v_add_co_u32_e32 v20, vcc, s34, v16
	v_and_b32_e32 v9, 0x1000, v9
	s_nop 0
	v_addc_co_u32_e32 v21, vcc, 0, v17, vcc
	v_add_co_u32_e32 v16, vcc, s19, v16
	v_lshlrev_b32_e32 v24, 1, v11
	s_nop 0
	v_addc_co_u32_e32 v17, vcc, 0, v17, vcc
	v_add_co_u32_e32 v26, vcc, s34, v14
	s_nop 1
	v_addc_co_u32_e32 v27, vcc, 0, v15, vcc
	v_add_co_u32_e32 v28, vcc, s34, v16
	s_nop 1
	v_addc_co_u32_e32 v29, vcc, 0, v17, vcc
	global_load_dwordx4 v[236:239], v[18:19], off
	global_load_dwordx4 v[240:243], v[20:21], off
	global_load_dwordx4 v[102:105], v[14:15], off
	global_load_dwordx4 v[110:113], v[16:17], off
	global_load_dwordx4 v[244:247], v[26:27], off
	global_load_dwordx4 v[248:251], v[28:29], off
	v_and_b32_e32 v16, 48, v23
	v_mad_u64_u32 v[14:15], s[20:21], v8, s3, v[10:11]
	v_lshl_or_b32 v8, v8, 6, v16
	v_lshlrev_b32_e32 v25, 3, v11
	v_add_u32_e32 v155, 0, v14
	v_add_u32_e32 v8, v8, v9
	v_and_b32_e32 v18, 32, v24
	v_add_u32_e32 v156, 0, v8
	v_mul_u32_u24_e32 v17, 0x48, v153
	v_lshlrev_b32_e32 v15, 1, v17
	v_mov_b32_e32 v116, 0
	s_mov_b32 s12, 0
	v_and_b32_e32 v154, 63, v11
	v_add3_u32 v80, 0, v15, v80
	v_mov_b32_e32 v117, v116
	v_mov_b32_e32 v118, v116
	v_mov_b32_e32 v119, v116
	v_mov_b32_e32 v8, v116
	v_mov_b32_e32 v9, v116
	v_mov_b32_e32 v14, v116
	v_mov_b32_e32 v15, v116
	v_mov_b32_e32 v16, v116
	v_mov_b32_e32 v17, v116
	s_waitcnt vmcnt(7)
	ds_write_b128 v155, v[0:3]
	s_waitcnt vmcnt(6)
	ds_write_b128 v156, v[4:7] offset:9216
	s_waitcnt vmcnt(5)
	ds_write_b128 v155, v[236:239] offset:17408
	s_waitcnt vmcnt(4)
	ds_write_b128 v156, v[240:243] offset:26624
	v_and_b32_e32 v0, 24, v25
	v_add3_u32 v2, 0, v18, v0
	v_lshrrev_b32_e32 v0, 3, v11
	v_bfe_u32 v1, v11, 2, 2
	v_and_or_b32 v0, v0, 4, v1
	v_lshlrev_b32_e32 v3, 6, v0
	v_lshl_add_u64 v[0:1], s[44:45], 0, v[12:13]
	v_xor_b32_e32 v32, 0x80000000, v22
	v_or3_b32 v0, v0, s24, v10
	v_mov_b32_e32 v33, v32
	v_mov_b32_e32 v34, v32
	v_mov_b32_e32 v35, v32
	v_mov_b32_e32 v36, v32
	v_mov_b32_e32 v37, v32
	v_mov_b32_e32 v38, v32
	v_mov_b32_e32 v39, v32
	v_mov_b32_e32 v40, v32
	v_mov_b32_e32 v41, v32
	v_mov_b32_e32 v42, v32
	v_mov_b32_e32 v43, v32
	v_mov_b32_e32 v44, v32
	v_mov_b32_e32 v45, v32
	v_mov_b32_e32 v46, v32
	v_mov_b32_e32 v47, v32
	v_lshl_add_u64 v[114:115], s[42:43], 0, v[0:1]
	v_add_u32_e32 v157, v2, v3
	v_add_u32_e32 v209, 0x8800, v157
	v_add_u32_e32 v208, 0x8800, v80
	v_add_co_u32_e32 v0, vcc, 0xffc00000, v114
	s_nop 1
	v_addc_co_u32_e32 v1, vcc, -1, v115, vcc
	v_add_co_u32_e32 v2, vcc, 0xffc04000, v114
	s_nop 1
	v_addc_co_u32_e32 v3, vcc, -1, v115, vcc
	v_add_co_u32_e32 v4, vcc, 0x4000, v114
	s_nop 1
	v_addc_co_u32_e32 v5, vcc, 0, v115, vcc
	global_load_dwordx4 v[98:101], v[0:1], off
	global_load_dwordx4 v[106:109], v[114:115], off
	global_load_dwordx4 v[236:239], v[2:3], off
	global_load_dwordx4 v[240:243], v[4:5], off
	v_lshl_add_u64 v[114:115], v[114:115], 0, s[14:15]
	v_lshl_add_u64 v[114:115], v[114:115], 0, s[14:15]
	v_mov_b32_e32 v0, v116
	v_mov_b32_e32 v1, v116
	v_mov_b32_e32 v2, v116
	v_mov_b32_e32 v3, v116
	v_mov_b32_e32 v4, v116
	v_mov_b32_e32 v5, v116
	v_mov_b32_e32 v6, v116
	v_mov_b32_e32 v7, v116
	v_mov_b32_e32 v10, v116
	v_mov_b32_e32 v11, v116
	v_mov_b32_e32 v12, v116
	v_mov_b32_e32 v13, v116
	v_mov_b32_e32 v18, v116
	v_mov_b32_e32 v19, v116
	v_mov_b32_e32 v20, v116
	v_mov_b32_e32 v21, v116
	v_mov_b32_e32 v22, v116
	v_mov_b32_e32 v23, v116
	v_mov_b32_e32 v24, v116
	v_mov_b32_e32 v25, v116
	v_mov_b32_e32 v26, v116
	v_mov_b32_e32 v27, v116
	v_mov_b32_e32 v28, v116
	v_mov_b32_e32 v29, v116
	v_mov_b32_e32 v30, v116
	v_mov_b32_e32 v31, v116
	s_waitcnt lgkmcnt(0)
	s_barrier
	s_branch .LBB0_847
.LBB0_846:
	s_add_i32 s12, s12, 2
	v_lshl_add_u64 v[114:115], v[114:115], 0, s[14:15]
	v_lshl_add_u64 v[114:115], v[114:115], 0, s[14:15]
	s_and_b64 vcc, exec, s[44:45]
	s_waitcnt lgkmcnt(0)
	s_barrier
	s_cbranch_vccnz .LBB0_852
; __device__ __forceinline__ void at_qk(f32x16& p0, f32x16& p1, const bf16_t* Ks, const bf16x8* qr, int r32, int hi) {
;     bf16x8 kf[8];
; #pragma unroll
;     for (int ds = 0; ds < 4; ++ds) {
;         kf[2 * ds] = *(const bf16x8*)(Ks + r32 * 72 + ds * 16 + hi * 8);
;         kf[2 * ds + 1] = *(const bf16x8*)(Ks + (r32 + 32) * 72 + ds * 16 + hi * 8);
;     }
;     __builtin_amdgcn_sched_barrier(0);
;     __builtin_amdgcn_s_setprio(1);
; #pragma unroll
;     for (int ds = 0; ds < 4; ++ds) {
;         p0 = __builtin_amdgcn_mfma_f32_32x32x16_bf16(kf[2 * ds], qr[ds], p0, 0, 0, 0);
;         p1 = __builtin_amdgcn_mfma_f32_32x32x16_bf16(kf[2 * ds + 1], qr[ds], p1, 0, 0, 0);
;     }
;     __builtin_amdgcn_s_setprio(0);
;     __builtin_amdgcn_sched_barrier(0);
; __device__ __forceinline__ void at_ldv(bf16x8 (&v0)[4], bf16x8 (&v1)[4], const unsigned char* Vs, int lane) {
;     const int hi = lane >> 5;
;     const unsigned char* vb = Vs + ((lane >> 4) & 1) * 32 + (lane & 3) * 8 + (4 * hi + ((lane & 15) >> 2)) * 64;
; #pragma unroll
;     for (int s = 0; s < 4; ++s) {
;         v0[s] = cat8(tr16(vb + s * 1024), tr16(vb + s * 1024 + 512));
;         v1[s] = cat8(tr16(vb + 4096 + s * 1024), tr16(vb + 4096 + s * 1024 + 512));
;     }
; }
; __device__ __forceinline__ void at_pv2(f32x16& o0, f32x16& o1, const f32x16& p0, const f32x16& p1, const bf16x8 (&v0)[4], const bf16x8 (&v1)[4]) {
;     bf16x8 pa[4];
; #pragma unroll
;     for (int s = 0; s < 4; ++s) {
;         u32x4 pw;
;         if (s < 2) { pw.x = pk2(p0[8 * s + 0], p0[8 * s + 1]); pw.y = pk2(p0[8 * s + 2], p0[8 * s + 3]); pw.z = pk2(p0[8 * s + 4], p0[8 * s + 5]); pw.w = pk2(p0[8 * s + 6], p0[8 * s + 7]); }
;         else { const int q = s - 2; pw.x = pk2(p1[8 * q + 0], p1[8 * q + 1]); pw.y = pk2(p1[8 * q + 2], p1[8 * q + 3]); pw.z = pk2(p1[8 * q + 4], p1[8 * q + 5]); pw.w = pk2(p1[8 * q + 6], p1[8 * q + 7]); }
;         pa[s] = __builtin_bit_cast(bf16x8, pw);
;     }
;     __builtin_amdgcn_sched_barrier(0);
;     __builtin_amdgcn_s_setprio(1);
; #pragma unroll
;     for (int s = 0; s < 4; ++s) {
;         o0 = __builtin_amdgcn_mfma_f32_32x32x16_bf16(pa[s], v0[s], o0, 0, 0, 0);
;         o1 = __builtin_amdgcn_mfma_f32_32x32x16_bf16(pa[s], v1[s], o1, 0, 0, 0);
;     }
;     __builtin_amdgcn_s_setprio(0);
;     __builtin_amdgcn_sched_barrier(0);
; }
.LBB0_847:
	ds_read_b128 v[64:67], v80
	ds_read_b128 v[120:123], v80 offset:32
	ds_read_b128 v[124:127], v80 offset:4608
	ds_read_b128 v[128:131], v80 offset:4640
	ds_read_b128 v[132:135], v80 offset:64
	ds_read_b128 v[136:139], v80 offset:96
	ds_read_b128 v[140:143], v80 offset:4672
	ds_read_b128 v[144:147], v80 offset:4704
	s_setprio 1
	s_waitcnt lgkmcnt(7)
	v_mfma_f32_32x32x16_bf16 v[48:63], v[64:67], v[82:85], v[32:47]
	s_waitcnt lgkmcnt(5)
	v_mfma_f32_32x32x16_bf16 v[64:79], v[124:127], v[82:85], v[32:47]
	v_mfma_f32_32x32x16_bf16 v[48:63], v[120:123], v[86:89], v[48:63]
	s_waitcnt lgkmcnt(4)
	v_mfma_f32_32x32x16_bf16 v[64:79], v[128:131], v[86:89], v[64:79]
	s_waitcnt lgkmcnt(3)
	v_mfma_f32_32x32x16_bf16 v[48:63], v[132:135], v[90:93], v[48:63]
	s_waitcnt lgkmcnt(1)
	v_mfma_f32_32x32x16_bf16 v[64:79], v[140:143], v[90:93], v[64:79]
	v_mfma_f32_32x32x16_bf16 v[48:63], v[136:139], v[94:97], v[48:63]
	s_waitcnt lgkmcnt(0)
	v_mfma_f32_32x32x16_bf16 v[64:79], v[144:147], v[94:97], v[64:79]
	s_setprio 0
	ds_read_b64_tr_b16 v[158:159], v157 offset:9216
	ds_read_b64_tr_b16 v[160:161], v157 offset:9728
	ds_read_b64_tr_b16 v[162:163], v157 offset:10240
	ds_read_b64_tr_b16 v[164:165], v157 offset:10752
	ds_read_b64_tr_b16 v[166:167], v157 offset:13312
	ds_read_b64_tr_b16 v[168:169], v157 offset:13824
	ds_read_b64_tr_b16 v[170:171], v157 offset:14336
	ds_read_b64_tr_b16 v[172:173], v157 offset:14848
	ds_read_b64_tr_b16 v[174:175], v157 offset:11264
	ds_read_b64_tr_b16 v[176:177], v157 offset:11776
	ds_read_b64_tr_b16 v[180:181], v157 offset:12288
	ds_read_b64_tr_b16 v[182:183], v157 offset:12800
	ds_read_b64_tr_b16 v[184:185], v157 offset:15360
	ds_read_b64_tr_b16 v[186:187], v157 offset:15872
	ds_read_b64_tr_b16 v[188:189], v157 offset:16384
	ds_read_b64_tr_b16 v[190:191], v157 offset:16896
	v_exp_f32_e32 v150, v48
	v_exp_f32_e32 v136, v64
	v_exp_f32_e32 v151, v49
	v_exp_f32_e32 v137, v65
	v_exp_f32_e32 v148, v50
	v_exp_f32_e32 v146, v66
	v_exp_f32_e32 v149, v51
	v_exp_f32_e32 v147, v67
	v_exp_f32_e32 v142, v52
	v_exp_f32_e32 v128, v68
	v_exp_f32_e32 v143, v53
	v_exp_f32_e32 v129, v69
	v_exp_f32_e32 v144, v54
	v_exp_f32_e32 v140, v70
	v_exp_f32_e32 v145, v55
	v_exp_f32_e32 v141, v71
	v_exp_f32_e32 v134, v56
	v_exp_f32_e32 v122, v72
	v_exp_f32_e32 v135, v57
	v_exp_f32_e32 v123, v73
	v_exp_f32_e32 v138, v58
	v_exp_f32_e32 v132, v74
	v_exp_f32_e32 v139, v59
	v_exp_f32_e32 v133, v75
	v_exp_f32_e32 v126, v60
	v_exp_f32_e32 v120, v76
	v_exp_f32_e32 v127, v61
	v_exp_f32_e32 v121, v77
	v_exp_f32_e32 v130, v62
	v_exp_f32_e32 v124, v78
	v_exp_f32_e32 v131, v63
	v_exp_f32_e32 v125, v79
	v_cvt_pk_bf16_f32 v48, v122, v123
	v_cvt_pk_bf16_f32 v49, v132, v133
	v_cvt_pk_bf16_f32 v50, v120, v121
	v_cvt_pk_bf16_f32 v51, v124, v125
	v_cvt_pk_bf16_f32 v52, v136, v137
	v_cvt_pk_bf16_f32 v53, v146, v147
	v_cvt_pk_bf16_f32 v54, v128, v129
	v_cvt_pk_bf16_f32 v55, v140, v141
	v_cvt_pk_bf16_f32 v56, v134, v135
	v_cvt_pk_bf16_f32 v57, v138, v139
	v_cvt_pk_bf16_f32 v58, v126, v127
	v_cvt_pk_bf16_f32 v59, v130, v131
	v_cvt_pk_bf16_f32 v60, v150, v151
	v_cvt_pk_bf16_f32 v61, v148, v149
	v_cvt_pk_bf16_f32 v62, v142, v143
	v_cvt_pk_bf16_f32 v63, v144, v145
	s_setprio 1
	s_waitcnt lgkmcnt(14)
	v_mfma_f32_32x32x16_bf16 v[0:15], v[60:63], v[158:161], v[0:15]
	s_waitcnt lgkmcnt(10)
	v_mfma_f32_32x32x16_bf16 v[16:31], v[60:63], v[166:169], v[16:31]
	v_mfma_f32_32x32x16_bf16 v[0:15], v[56:59], v[162:165], v[0:15]
	s_waitcnt lgkmcnt(8)
	v_mfma_f32_32x32x16_bf16 v[16:31], v[56:59], v[170:173], v[16:31]
	s_waitcnt lgkmcnt(6)
	v_mfma_f32_32x32x16_bf16 v[0:15], v[52:55], v[174:177], v[0:15]
	s_waitcnt lgkmcnt(2)
	v_mfma_f32_32x32x16_bf16 v[16:31], v[52:55], v[184:187], v[16:31]
	v_mfma_f32_32x32x16_bf16 v[0:15], v[48:51], v[180:183], v[0:15]
	s_waitcnt lgkmcnt(0)
	v_mfma_f32_32x32x16_bf16 v[16:31], v[48:51], v[188:191], v[16:31]
	s_setprio 0
	s_nop 7
	ds_read_b128 v[48:51], v80 offset:17408
	ds_read_b128 v[158:161], v80 offset:17440
	ds_read_b128 v[162:165], v80 offset:22016
	ds_read_b128 v[166:169], v80 offset:22048
	ds_read_b128 v[170:173], v80 offset:17472
	ds_read_b128 v[174:177], v80 offset:17504
	ds_read_b128 v[180:183], v80 offset:22080
	ds_read_b128 v[184:187], v80 offset:22112
	s_setprio 1
	s_waitcnt lgkmcnt(7)
	v_mfma_f32_32x32x16_bf16 v[64:79], v[48:51], v[82:85], v[32:47]
	s_waitcnt lgkmcnt(5)
	v_mfma_f32_32x32x16_bf16 v[48:63], v[162:165], v[82:85], v[32:47]
	v_mfma_f32_32x32x16_bf16 v[64:79], v[158:161], v[86:89], v[64:79]
	s_waitcnt lgkmcnt(4)
	v_mfma_f32_32x32x16_bf16 v[48:63], v[166:169], v[86:89], v[48:63]
	s_waitcnt lgkmcnt(3)
	v_mfma_f32_32x32x16_bf16 v[64:79], v[170:173], v[90:93], v[64:79]
	s_waitcnt lgkmcnt(1)
	v_mfma_f32_32x32x16_bf16 v[48:63], v[180:183], v[90:93], v[48:63]
	v_mfma_f32_32x32x16_bf16 v[64:79], v[174:177], v[94:97], v[64:79]
	s_waitcnt lgkmcnt(0)
; __device__ __forceinline__ unsigned pk2(float lo, float hi) { f32x2 v = {lo, hi}; bf16x2_t b = __builtin_convertvector(v, bf16x2_t); return __builtin_bit_cast(unsigned, b); }
; __device__ __forceinline__ void at_ldv(bf16x8 (&v0)[4], bf16x8 (&v1)[4], const unsigned char* Vs, int lane) {
;     const int hi = lane >> 5;
;     const unsigned char* vb = Vs + ((lane >> 4) & 1) * 32 + (lane & 3) * 8 + (4 * hi + ((lane & 15) >> 2)) * 64;
; #pragma unroll
;     for (int s = 0; s < 4; ++s) {
;         v0[s] = cat8(tr16(vb + s * 1024), tr16(vb + s * 1024 + 512));
;         v1[s] = cat8(tr16(vb + 4096 + s * 1024), tr16(vb + 4096 + s * 1024 + 512));
;     }
; }
; __device__ __forceinline__ void at_pv2(f32x16& o0, f32x16& o1, const f32x16& p0, const f32x16& p1, const bf16x8 (&v0)[4], const bf16x8 (&v1)[4]) {
;     bf16x8 pa[4];
; #pragma unroll
;     for (int s = 0; s < 4; ++s) {
;         u32x4 pw;
;         if (s < 2) { pw.x = pk2(p0[8 * s + 0], p0[8 * s + 1]); pw.y = pk2(p0[8 * s + 2], p0[8 * s + 3]); pw.z = pk2(p0[8 * s + 4], p0[8 * s + 5]); pw.w = pk2(p0[8 * s + 6], p0[8 * s + 7]); }
;         else { const int q = s - 2; pw.x = pk2(p1[8 * q + 0], p1[8 * q + 1]); pw.y = pk2(p1[8 * q + 2], p1[8 * q + 3]); pw.z = pk2(p1[8 * q + 4], p1[8 * q + 5]); pw.w = pk2(p1[8 * q + 6], p1[8 * q + 7]); }
;         pa[s] = __builtin_bit_cast(bf16x8, pw);
;     }
;     __builtin_amdgcn_sched_barrier(0);
;     __builtin_amdgcn_s_setprio(1);
; #pragma unroll
;     for (int s = 0; s < 4; ++s) {
;         o0 = __builtin_amdgcn_mfma_f32_32x32x16_bf16(pa[s], v0[s], o0, 0, 0, 0);
;         o1 = __builtin_amdgcn_mfma_f32_32x32x16_bf16(pa[s], v1[s], o1, 0, 0, 0);
;     }
;     __builtin_amdgcn_s_setprio(0);
;     __builtin_amdgcn_sched_barrier(0);
; }
; __device__ void attn_a_item(const Params& p, int item, int l, unsigned char* smem) {
;     ...
;     __syncthreads();
;     ATA_LOAD(rkA, rvA, 0); ATA_LOAD(rkB, rvB, 1);
;     ATA_STORE(rkA, rvA, 0);
;     ATA_LOAD(rkA, rvA, 2);
;     __syncthreads();
;     for (int kt = 0; kt < NT; kt += 2) {
;         ATA_COMPUTE(0);
;         ATA_STORE(rkB, rvB, 1);
;         if (kt + 3 < NT) ATA_LOAD(rkB, rvB, kt + 3);
;         __syncthreads();
;         ATA_COMPUTE(1);
;         if (kt + 2 < NT) { ATA_STORE(rkA, rvA, 0); if (kt + 4 < NT) ATA_LOAD(rkA, rvA, kt + 4); }
	v_mfma_f32_32x32x16_bf16 v[48:63], v[184:187], v[94:97], v[48:63]
	s_setprio 0
	ds_read_b64_tr_b16 v[158:159], v157 offset:26624
	ds_read_b64_tr_b16 v[160:161], v157 offset:27136
	ds_read_b64_tr_b16 v[162:163], v157 offset:27648
	ds_read_b64_tr_b16 v[164:165], v157 offset:28160
	ds_read_b64_tr_b16 v[166:167], v157 offset:30720
	ds_read_b64_tr_b16 v[168:169], v157 offset:31232
	ds_read_b64_tr_b16 v[170:171], v157 offset:31744
	ds_read_b64_tr_b16 v[172:173], v157 offset:32256
	ds_read_b64_tr_b16 v[174:175], v157 offset:28672
	ds_read_b64_tr_b16 v[176:177], v157 offset:29184
	ds_read_b64_tr_b16 v[180:181], v157 offset:29696
	ds_read_b64_tr_b16 v[182:183], v157 offset:30208
	ds_read_b64_tr_b16 v[184:185], v157 offset:32768
	ds_read_b64_tr_b16 v[186:187], v157 offset:33280
	ds_read_b64_tr_b16 v[188:189], v157 offset:33792
	ds_read_b64_tr_b16 v[190:191], v157 offset:34304
	v_exp_f32_e32 v64, v64
	v_exp_f32_e32 v48, v48
	v_exp_f32_e32 v65, v65
	v_exp_f32_e32 v49, v49
	v_exp_f32_e32 v66, v66
	v_exp_f32_e32 v50, v50
	v_exp_f32_e32 v67, v67
	v_exp_f32_e32 v51, v51
	v_exp_f32_e32 v68, v68
	v_exp_f32_e32 v52, v52
	v_exp_f32_e32 v69, v69
	v_exp_f32_e32 v53, v53
	v_exp_f32_e32 v70, v70
	v_exp_f32_e32 v54, v54
	v_exp_f32_e32 v71, v71
	v_exp_f32_e32 v55, v55
	v_exp_f32_e32 v72, v72
	v_exp_f32_e32 v56, v56
	v_exp_f32_e32 v73, v73
	v_exp_f32_e32 v57, v57
	v_exp_f32_e32 v74, v74
	v_exp_f32_e32 v58, v58
	v_exp_f32_e32 v75, v75
	v_exp_f32_e32 v59, v59
	v_exp_f32_e32 v76, v76
	v_exp_f32_e32 v60, v60
	v_exp_f32_e32 v77, v77
	v_exp_f32_e32 v61, v61
	v_exp_f32_e32 v78, v78
	v_exp_f32_e32 v62, v62
	v_exp_f32_e32 v79, v79
	v_exp_f32_e32 v63, v63
	v_cvt_pk_bf16_f32 v192, v56, v57
	v_cvt_pk_bf16_f32 v193, v58, v59
	v_cvt_pk_bf16_f32 v194, v60, v61
	v_cvt_pk_bf16_f32 v195, v62, v63
	v_cvt_pk_bf16_f32 v196, v48, v49
	v_cvt_pk_bf16_f32 v197, v50, v51
	v_cvt_pk_bf16_f32 v198, v52, v53
	v_cvt_pk_bf16_f32 v199, v54, v55
	v_cvt_pk_bf16_f32 v200, v72, v73
	v_cvt_pk_bf16_f32 v201, v74, v75
	v_cvt_pk_bf16_f32 v202, v76, v77
	v_cvt_pk_bf16_f32 v203, v78, v79
	v_cvt_pk_bf16_f32 v204, v64, v65
	v_cvt_pk_bf16_f32 v205, v66, v67
	v_cvt_pk_bf16_f32 v206, v68, v69
	v_cvt_pk_bf16_f32 v207, v70, v71
	s_setprio 1
	s_waitcnt lgkmcnt(14)
	v_mfma_f32_32x32x16_bf16 v[0:15], v[204:207], v[158:161], v[0:15]
	s_waitcnt lgkmcnt(10)
	v_mfma_f32_32x32x16_bf16 v[16:31], v[204:207], v[166:169], v[16:31]
	v_mfma_f32_32x32x16_bf16 v[0:15], v[200:203], v[162:165], v[0:15]
	s_waitcnt lgkmcnt(8)
	v_mfma_f32_32x32x16_bf16 v[16:31], v[200:203], v[170:173], v[16:31]
	s_waitcnt lgkmcnt(6)
	v_mfma_f32_32x32x16_bf16 v[0:15], v[196:199], v[174:177], v[0:15]
	s_waitcnt lgkmcnt(2)
	v_mfma_f32_32x32x16_bf16 v[16:31], v[196:199], v[184:187], v[16:31]
	v_mfma_f32_32x32x16_bf16 v[0:15], v[192:195], v[180:183], v[0:15]
	s_waitcnt lgkmcnt(0)
	v_mfma_f32_32x32x16_bf16 v[16:31], v[192:195], v[188:191], v[16:31]
	s_setprio 0
	v_pk_add_f32 v[116:117], v[116:117], v[150:151]
	v_pk_add_f32 v[118:119], v[118:119], v[148:149]
	v_pk_add_f32 v[116:117], v[136:137], v[116:117]
	v_pk_add_f32 v[118:119], v[146:147], v[118:119]
	v_pk_add_f32 v[116:117], v[142:143], v[116:117]
	v_pk_add_f32 v[118:119], v[144:145], v[118:119]
	v_pk_add_f32 v[116:117], v[128:129], v[116:117]
	v_pk_add_f32 v[118:119], v[140:141], v[118:119]
	v_pk_add_f32 v[116:117], v[134:135], v[116:117]
	v_pk_add_f32 v[118:119], v[138:139], v[118:119]
	v_pk_add_f32 v[116:117], v[122:123], v[116:117]
	v_pk_add_f32 v[118:119], v[132:133], v[118:119]
	v_pk_add_f32 v[116:117], v[126:127], v[116:117]
	v_pk_add_f32 v[118:119], v[130:131], v[118:119]
	v_pk_add_f32 v[116:117], v[120:121], v[116:117]
	v_pk_add_f32 v[118:119], v[124:125], v[118:119]
	v_pk_add_f32 v[64:65], v[116:117], v[64:65]
	v_pk_add_f32 v[66:67], v[118:119], v[66:67]
	v_pk_add_f32 v[48:49], v[48:49], v[64:65]
	v_pk_add_f32 v[50:51], v[50:51], v[66:67]
	v_pk_add_f32 v[48:49], v[68:69], v[48:49]
	v_pk_add_f32 v[50:51], v[70:71], v[50:51]
	v_pk_add_f32 v[48:49], v[52:53], v[48:49]
	v_pk_add_f32 v[50:51], v[54:55], v[50:51]
	v_pk_add_f32 v[48:49], v[72:73], v[48:49]
	v_pk_add_f32 v[50:51], v[74:75], v[50:51]
	v_pk_add_f32 v[48:49], v[56:57], v[48:49]
	v_pk_add_f32 v[50:51], v[58:59], v[50:51]
	v_pk_add_f32 v[48:49], v[76:77], v[48:49]
	v_pk_add_f32 v[50:51], v[78:79], v[50:51]
	v_pk_add_f32 v[116:117], v[60:61], v[48:49]
	v_pk_add_f32 v[118:119], v[62:63], v[50:51]
	s_waitcnt vmcnt(0)
	ds_write_b128 v155, v[102:105] offset:34816
	ds_write_b128 v156, v[110:113] offset:44032
	ds_write_b128 v155, v[244:247] offset:52224
	ds_write_b128 v156, v[248:251] offset:61440
	s_cmpk_lt_u32 s12, 61
	s_cbranch_scc0 .Lst_mid_noload
	v_add_co_u32_e32 v48, vcc, 0xffbf8000, v114
	s_nop 1
	v_addc_co_u32_e32 v49, vcc, -1, v115, vcc
	v_add_co_u32_e32 v50, vcc, 0xffff8000, v114
	s_nop 1
	v_addc_co_u32_e32 v51, vcc, -1, v115, vcc
	v_add_co_u32_e32 v52, vcc, 0xffbfc000, v114
	s_nop 1
	v_addc_co_u32_e32 v53, vcc, -1, v115, vcc
	v_add_co_u32_e32 v54, vcc, 0xffffc000, v114
	s_nop 1
	v_addc_co_u32_e32 v55, vcc, -1, v115, vcc
	global_load_dwordx4 v[102:105], v[48:49], off
	global_load_dwordx4 v[110:113], v[50:51], off
	global_load_dwordx4 v[244:247], v[52:53], off
	global_load_dwordx4 v[248:251], v[54:55], off
; __device__ __forceinline__ void at_qk(f32x16& p0, f32x16& p1, const bf16_t* Ks, const bf16x8* qr, int r32, int hi) {
;     bf16x8 kf[8];
; #pragma unroll
;     for (int ds = 0; ds < 4; ++ds) {
;         kf[2 * ds] = *(const bf16x8*)(Ks + r32 * 72 + ds * 16 + hi * 8);
;         kf[2 * ds + 1] = *(const bf16x8*)(Ks + (r32 + 32) * 72 + ds * 16 + hi * 8);
;     }
;     __builtin_amdgcn_sched_barrier(0);
;     __builtin_amdgcn_s_setprio(1);
; #pragma unroll
;     for (int ds = 0; ds < 4; ++ds) {
;         p0 = __builtin_amdgcn_mfma_f32_32x32x16_bf16(kf[2 * ds], qr[ds], p0, 0, 0, 0);
;         p1 = __builtin_amdgcn_mfma_f32_32x32x16_bf16(kf[2 * ds + 1], qr[ds], p1, 0, 0, 0);
;     }
;     __builtin_amdgcn_s_setprio(0);
;     __builtin_amdgcn_sched_barrier(0);
; __device__ __forceinline__ void at_ldv(bf16x8 (&v0)[4], bf16x8 (&v1)[4], const unsigned char* Vs, int lane) {
;     const int hi = lane >> 5;
;     const unsigned char* vb = Vs + ((lane >> 4) & 1) * 32 + (lane & 3) * 8 + (4 * hi + ((lane & 15) >> 2)) * 64;
; #pragma unroll
;     for (int s = 0; s < 4; ++s) {
;         v0[s] = cat8(tr16(vb + s * 1024), tr16(vb + s * 1024 + 512));
;         v1[s] = cat8(tr16(vb + 4096 + s * 1024), tr16(vb + 4096 + s * 1024 + 512));
;     }
; }
; __device__ __forceinline__ void at_pv2(f32x16& o0, f32x16& o1, const f32x16& p0, const f32x16& p1, const bf16x8 (&v0)[4], const bf16x8 (&v1)[4]) {
;     bf16x8 pa[4];
; #pragma unroll
;     for (int s = 0; s < 4; ++s) {
;         u32x4 pw;
;         if (s < 2) { pw.x = pk2(p0[8 * s + 0], p0[8 * s + 1]); pw.y = pk2(p0[8 * s + 2], p0[8 * s + 3]); pw.z = pk2(p0[8 * s + 4], p0[8 * s + 5]); pw.w = pk2(p0[8 * s + 6], p0[8 * s + 7]); }
;         else { const int q = s - 2; pw.x = pk2(p1[8 * q + 0], p1[8 * q + 1]); pw.y = pk2(p1[8 * q + 2], p1[8 * q + 3]); pw.z = pk2(p1[8 * q + 4], p1[8 * q + 5]); pw.w = pk2(p1[8 * q + 6], p1[8 * q + 7]); }
;         pa[s] = __builtin_bit_cast(bf16x8, pw);
;     }
;     __builtin_amdgcn_sched_barrier(0);
;     __builtin_amdgcn_s_setprio(1);
; #pragma unroll
;     for (int s = 0; s < 4; ++s) {
;         o0 = __builtin_amdgcn_mfma_f32_32x32x16_bf16(pa[s], v0[s], o0, 0, 0, 0);
;         o1 = __builtin_amdgcn_mfma_f32_32x32x16_bf16(pa[s], v1[s], o1, 0, 0, 0);
;     }
;     __builtin_amdgcn_s_setprio(0);
;     __builtin_amdgcn_sched_barrier(0);
; }
.Lst_mid_noload:
	s_waitcnt lgkmcnt(0)
	s_barrier
	ds_read_b128 v[64:67], v208
	ds_read_b128 v[120:123], v208 offset:32
	ds_read_b128 v[124:127], v208 offset:4608
	ds_read_b128 v[128:131], v208 offset:4640
	ds_read_b128 v[132:135], v208 offset:64
	ds_read_b128 v[136:139], v208 offset:96
	ds_read_b128 v[140:143], v208 offset:4672
	ds_read_b128 v[144:147], v208 offset:4704
	s_setprio 1
	s_waitcnt lgkmcnt(7)
	v_mfma_f32_32x32x16_bf16 v[48:63], v[64:67], v[82:85], v[32:47]
	s_waitcnt lgkmcnt(5)
	v_mfma_f32_32x32x16_bf16 v[64:79], v[124:127], v[82:85], v[32:47]
	v_mfma_f32_32x32x16_bf16 v[48:63], v[120:123], v[86:89], v[48:63]
	s_waitcnt lgkmcnt(4)
	v_mfma_f32_32x32x16_bf16 v[64:79], v[128:131], v[86:89], v[64:79]
	s_waitcnt lgkmcnt(3)
	v_mfma_f32_32x32x16_bf16 v[48:63], v[132:135], v[90:93], v[48:63]
	s_waitcnt lgkmcnt(1)
	v_mfma_f32_32x32x16_bf16 v[64:79], v[140:143], v[90:93], v[64:79]
	v_mfma_f32_32x32x16_bf16 v[48:63], v[136:139], v[94:97], v[48:63]
	s_waitcnt lgkmcnt(0)
	v_mfma_f32_32x32x16_bf16 v[64:79], v[144:147], v[94:97], v[64:79]
	s_setprio 0
	ds_read_b64_tr_b16 v[158:159], v209 offset:9216
	ds_read_b64_tr_b16 v[160:161], v209 offset:9728
	ds_read_b64_tr_b16 v[162:163], v209 offset:10240
	ds_read_b64_tr_b16 v[164:165], v209 offset:10752
	ds_read_b64_tr_b16 v[166:167], v209 offset:13312
	ds_read_b64_tr_b16 v[168:169], v209 offset:13824
	ds_read_b64_tr_b16 v[170:171], v209 offset:14336
	ds_read_b64_tr_b16 v[172:173], v209 offset:14848
	ds_read_b64_tr_b16 v[174:175], v209 offset:11264
	ds_read_b64_tr_b16 v[176:177], v209 offset:11776
	ds_read_b64_tr_b16 v[180:181], v209 offset:12288
	ds_read_b64_tr_b16 v[182:183], v209 offset:12800
	ds_read_b64_tr_b16 v[184:185], v209 offset:15360
	ds_read_b64_tr_b16 v[186:187], v209 offset:15872
	ds_read_b64_tr_b16 v[188:189], v209 offset:16384
	ds_read_b64_tr_b16 v[190:191], v209 offset:16896
	v_exp_f32_e32 v150, v48
	v_exp_f32_e32 v136, v64
	v_exp_f32_e32 v151, v49
	v_exp_f32_e32 v137, v65
	v_exp_f32_e32 v148, v50
	v_exp_f32_e32 v146, v66
	v_exp_f32_e32 v149, v51
	v_exp_f32_e32 v147, v67
	v_exp_f32_e32 v142, v52
	v_exp_f32_e32 v128, v68
	v_exp_f32_e32 v143, v53
	v_exp_f32_e32 v129, v69
	v_exp_f32_e32 v144, v54
	v_exp_f32_e32 v140, v70
	v_exp_f32_e32 v145, v55
	v_exp_f32_e32 v141, v71
	v_exp_f32_e32 v134, v56
	v_exp_f32_e32 v122, v72
	v_exp_f32_e32 v135, v57
	v_exp_f32_e32 v123, v73
	v_exp_f32_e32 v138, v58
	v_exp_f32_e32 v132, v74
	v_exp_f32_e32 v139, v59
	v_exp_f32_e32 v133, v75
	v_exp_f32_e32 v126, v60
	v_exp_f32_e32 v120, v76
	v_exp_f32_e32 v127, v61
	v_exp_f32_e32 v121, v77
	v_exp_f32_e32 v130, v62
	v_exp_f32_e32 v124, v78
	v_exp_f32_e32 v131, v63
	v_exp_f32_e32 v125, v79
	v_cvt_pk_bf16_f32 v48, v122, v123
	v_cvt_pk_bf16_f32 v49, v132, v133
	v_cvt_pk_bf16_f32 v50, v120, v121
	v_cvt_pk_bf16_f32 v51, v124, v125
	v_cvt_pk_bf16_f32 v52, v136, v137
	v_cvt_pk_bf16_f32 v53, v146, v147
	v_cvt_pk_bf16_f32 v54, v128, v129
	v_cvt_pk_bf16_f32 v55, v140, v141
	v_cvt_pk_bf16_f32 v56, v134, v135
	v_cvt_pk_bf16_f32 v57, v138, v139
	v_cvt_pk_bf16_f32 v58, v126, v127
	v_cvt_pk_bf16_f32 v59, v130, v131
	v_cvt_pk_bf16_f32 v60, v150, v151
	v_cvt_pk_bf16_f32 v61, v148, v149
	v_cvt_pk_bf16_f32 v62, v142, v143
	v_cvt_pk_bf16_f32 v63, v144, v145
	s_setprio 1
	s_waitcnt lgkmcnt(14)
	v_mfma_f32_32x32x16_bf16 v[0:15], v[60:63], v[158:161], v[0:15]
	s_waitcnt lgkmcnt(10)
	v_mfma_f32_32x32x16_bf16 v[16:31], v[60:63], v[166:169], v[16:31]
	v_mfma_f32_32x32x16_bf16 v[0:15], v[56:59], v[162:165], v[0:15]
	s_waitcnt lgkmcnt(8)
	v_mfma_f32_32x32x16_bf16 v[16:31], v[56:59], v[170:173], v[16:31]
	s_waitcnt lgkmcnt(6)
	v_mfma_f32_32x32x16_bf16 v[0:15], v[52:55], v[174:177], v[0:15]
	s_waitcnt lgkmcnt(2)
	v_mfma_f32_32x32x16_bf16 v[16:31], v[52:55], v[184:187], v[16:31]
	v_mfma_f32_32x32x16_bf16 v[0:15], v[48:51], v[180:183], v[0:15]
	s_waitcnt lgkmcnt(0)
	v_mfma_f32_32x32x16_bf16 v[16:31], v[48:51], v[188:191], v[16:31]
	s_setprio 0
	s_nop 7
	ds_read_b128 v[48:51], v208 offset:17408
	ds_read_b128 v[158:161], v208 offset:17440
	ds_read_b128 v[162:165], v208 offset:22016
	ds_read_b128 v[166:169], v208 offset:22048
	ds_read_b128 v[170:173], v208 offset:17472
	ds_read_b128 v[174:177], v208 offset:17504
	ds_read_b128 v[180:183], v208 offset:22080
	ds_read_b128 v[184:187], v208 offset:22112
	s_setprio 1
	s_waitcnt lgkmcnt(7)
	v_mfma_f32_32x32x16_bf16 v[64:79], v[48:51], v[82:85], v[32:47]
	s_waitcnt lgkmcnt(5)
	v_mfma_f32_32x32x16_bf16 v[48:63], v[162:165], v[82:85], v[32:47]
	v_mfma_f32_32x32x16_bf16 v[64:79], v[158:161], v[86:89], v[64:79]
	s_waitcnt lgkmcnt(4)
	v_mfma_f32_32x32x16_bf16 v[48:63], v[166:169], v[86:89], v[48:63]
	s_waitcnt lgkmcnt(3)
	v_mfma_f32_32x32x16_bf16 v[64:79], v[170:173], v[90:93], v[64:79]
	s_waitcnt lgkmcnt(1)
	v_mfma_f32_32x32x16_bf16 v[48:63], v[180:183], v[90:93], v[48:63]
	v_mfma_f32_32x32x16_bf16 v[64:79], v[174:177], v[94:97], v[64:79]
	s_waitcnt lgkmcnt(0)
; __device__ __forceinline__ unsigned pk2(float lo, float hi) { f32x2 v = {lo, hi}; bf16x2_t b = __builtin_convertvector(v, bf16x2_t); return __builtin_bit_cast(unsigned, b); }
; #define ATA_LOAD(RK, RV, t) do { const size_t tb = (size_t)(t) * 64 * 128; RK[0] = *(const u32x4*)(Kb + tb + goff0); RV[0] = *(const u32x4*)(Vb + tb + goff0); } while (0)
; #define ATA_STORE(RK, RV, st) do { unsigned char* sb_ = smem + (st) * ATA_STAGE; *(u32x4*)(sb_ + ko0) = RK[0]; *(u32x4*)(sb_ + vo0) = RV[0]; } while (0)
; __device__ __forceinline__ void at_pv2(f32x16& o0, f32x16& o1, const f32x16& p0, const f32x16& p1, const bf16x8 (&v0)[4], const bf16x8 (&v1)[4]) {
;     bf16x8 pa[4];
; #pragma unroll
;     for (int s = 0; s < 4; ++s) {
;         u32x4 pw;
;         if (s < 2) { pw.x = pk2(p0[8 * s + 0], p0[8 * s + 1]); pw.y = pk2(p0[8 * s + 2], p0[8 * s + 3]); pw.z = pk2(p0[8 * s + 4], p0[8 * s + 5]); pw.w = pk2(p0[8 * s + 6], p0[8 * s + 7]); }
;         else { const int q = s - 2; pw.x = pk2(p1[8 * q + 0], p1[8 * q + 1]); pw.y = pk2(p1[8 * q + 2], p1[8 * q + 3]); pw.z = pk2(p1[8 * q + 4], p1[8 * q + 5]); pw.w = pk2(p1[8 * q + 6], p1[8 * q + 7]); }
;         pa[s] = __builtin_bit_cast(bf16x8, pw);
;     }
;     __builtin_amdgcn_sched_barrier(0);
;     __builtin_amdgcn_s_setprio(1);
; #pragma unroll
;     for (int s = 0; s < 4; ++s) {
;         o0 = __builtin_amdgcn_mfma_f32_32x32x16_bf16(pa[s], v0[s], o0, 0, 0, 0);
;         o1 = __builtin_amdgcn_mfma_f32_32x32x16_bf16(pa[s], v1[s], o1, 0, 0, 0);
;     }
;     __builtin_amdgcn_s_setprio(0);
;     __builtin_amdgcn_sched_barrier(0);
; }
; __device__ void attn_a_item(const Params& p, int item, int l, unsigned char* smem) {
;     ...
;     __syncthreads();
;     ATA_LOAD(rkA, rvA, 0); ATA_LOAD(rkB, rvB, 1);
;     ATA_STORE(rkA, rvA, 0);
;     ATA_LOAD(rkA, rvA, 2);
;     __syncthreads();
;     for (int kt = 0; kt < NT; kt += 2) {
;         ATA_COMPUTE(0);
;         ATA_STORE(rkB, rvB, 1);
;         if (kt + 3 < NT) ATA_LOAD(rkB, rvB, kt + 3);
;         __syncthreads();
;         ATA_COMPUTE(1);
;         if (kt + 2 < NT) { ATA_STORE(rkA, rvA, 0); if (kt + 4 < NT) ATA_LOAD(rkA, rvA, kt + 4); }
;         __syncthreads();
;     }
	v_mfma_f32_32x32x16_bf16 v[48:63], v[184:187], v[94:97], v[48:63]
	s_setprio 0
	ds_read_b64_tr_b16 v[158:159], v209 offset:26624
	ds_read_b64_tr_b16 v[160:161], v209 offset:27136
	ds_read_b64_tr_b16 v[162:163], v209 offset:27648
	ds_read_b64_tr_b16 v[164:165], v209 offset:28160
	ds_read_b64_tr_b16 v[166:167], v209 offset:30720
	ds_read_b64_tr_b16 v[168:169], v209 offset:31232
	ds_read_b64_tr_b16 v[170:171], v209 offset:31744
	ds_read_b64_tr_b16 v[172:173], v209 offset:32256
	ds_read_b64_tr_b16 v[174:175], v209 offset:28672
	ds_read_b64_tr_b16 v[176:177], v209 offset:29184
	ds_read_b64_tr_b16 v[180:181], v209 offset:29696
	ds_read_b64_tr_b16 v[182:183], v209 offset:30208
	ds_read_b64_tr_b16 v[184:185], v209 offset:32768
	ds_read_b64_tr_b16 v[186:187], v209 offset:33280
	ds_read_b64_tr_b16 v[188:189], v209 offset:33792
	ds_read_b64_tr_b16 v[190:191], v209 offset:34304
	v_exp_f32_e32 v64, v64
	v_exp_f32_e32 v48, v48
	v_exp_f32_e32 v65, v65
	v_exp_f32_e32 v49, v49
	v_exp_f32_e32 v66, v66
	v_exp_f32_e32 v50, v50
	v_exp_f32_e32 v67, v67
	v_exp_f32_e32 v51, v51
	v_exp_f32_e32 v68, v68
	v_exp_f32_e32 v52, v52
	v_exp_f32_e32 v69, v69
	v_exp_f32_e32 v53, v53
	v_exp_f32_e32 v70, v70
	v_exp_f32_e32 v54, v54
	v_exp_f32_e32 v71, v71
	v_exp_f32_e32 v55, v55
	v_exp_f32_e32 v72, v72
	v_exp_f32_e32 v56, v56
	v_exp_f32_e32 v73, v73
	v_exp_f32_e32 v57, v57
	v_exp_f32_e32 v74, v74
	v_exp_f32_e32 v58, v58
	v_exp_f32_e32 v75, v75
	v_exp_f32_e32 v59, v59
	v_exp_f32_e32 v76, v76
	v_exp_f32_e32 v60, v60
	v_exp_f32_e32 v77, v77
	v_exp_f32_e32 v61, v61
	v_exp_f32_e32 v78, v78
	v_exp_f32_e32 v62, v62
	v_exp_f32_e32 v79, v79
	v_exp_f32_e32 v63, v63
	v_cvt_pk_bf16_f32 v192, v56, v57
	v_cvt_pk_bf16_f32 v193, v58, v59
	v_cvt_pk_bf16_f32 v194, v60, v61
	v_cvt_pk_bf16_f32 v195, v62, v63
	v_cvt_pk_bf16_f32 v196, v48, v49
	v_cvt_pk_bf16_f32 v197, v50, v51
	v_cvt_pk_bf16_f32 v198, v52, v53
	v_cvt_pk_bf16_f32 v199, v54, v55
	v_cvt_pk_bf16_f32 v200, v72, v73
	v_cvt_pk_bf16_f32 v201, v74, v75
	v_cvt_pk_bf16_f32 v202, v76, v77
	v_cvt_pk_bf16_f32 v203, v78, v79
	v_cvt_pk_bf16_f32 v204, v64, v65
	v_cvt_pk_bf16_f32 v205, v66, v67
	v_cvt_pk_bf16_f32 v206, v68, v69
	v_cvt_pk_bf16_f32 v207, v70, v71
	s_setprio 1
	s_waitcnt lgkmcnt(14)
	v_mfma_f32_32x32x16_bf16 v[0:15], v[204:207], v[158:161], v[0:15]
	s_waitcnt lgkmcnt(10)
	v_mfma_f32_32x32x16_bf16 v[16:31], v[204:207], v[166:169], v[16:31]
	v_mfma_f32_32x32x16_bf16 v[0:15], v[200:203], v[162:165], v[0:15]
	s_waitcnt lgkmcnt(8)
	v_mfma_f32_32x32x16_bf16 v[16:31], v[200:203], v[170:173], v[16:31]
	s_waitcnt lgkmcnt(6)
	v_mfma_f32_32x32x16_bf16 v[0:15], v[196:199], v[174:177], v[0:15]
	s_waitcnt lgkmcnt(2)
	v_mfma_f32_32x32x16_bf16 v[16:31], v[196:199], v[184:187], v[16:31]
	v_mfma_f32_32x32x16_bf16 v[0:15], v[192:195], v[180:183], v[0:15]
	s_waitcnt lgkmcnt(0)
	v_mfma_f32_32x32x16_bf16 v[16:31], v[192:195], v[188:191], v[16:31]
	s_setprio 0
	v_pk_add_f32 v[116:117], v[116:117], v[150:151]
	v_pk_add_f32 v[118:119], v[118:119], v[148:149]
	v_pk_add_f32 v[116:117], v[136:137], v[116:117]
	v_pk_add_f32 v[118:119], v[146:147], v[118:119]
	v_pk_add_f32 v[116:117], v[142:143], v[116:117]
	v_pk_add_f32 v[118:119], v[144:145], v[118:119]
	v_pk_add_f32 v[116:117], v[128:129], v[116:117]
	v_pk_add_f32 v[118:119], v[140:141], v[118:119]
	v_pk_add_f32 v[116:117], v[134:135], v[116:117]
	v_pk_add_f32 v[118:119], v[138:139], v[118:119]
	v_pk_add_f32 v[116:117], v[122:123], v[116:117]
	v_pk_add_f32 v[118:119], v[132:133], v[118:119]
	v_pk_add_f32 v[116:117], v[126:127], v[116:117]
	v_pk_add_f32 v[118:119], v[130:131], v[118:119]
	v_pk_add_f32 v[116:117], v[120:121], v[116:117]
	v_pk_add_f32 v[118:119], v[124:125], v[118:119]
	v_pk_add_f32 v[64:65], v[116:117], v[64:65]
	v_pk_add_f32 v[66:67], v[118:119], v[66:67]
	v_pk_add_f32 v[48:49], v[48:49], v[64:65]
	v_pk_add_f32 v[50:51], v[50:51], v[66:67]
	v_pk_add_f32 v[48:49], v[68:69], v[48:49]
	v_pk_add_f32 v[50:51], v[70:71], v[50:51]
	v_pk_add_f32 v[48:49], v[52:53], v[48:49]
	v_pk_add_f32 v[50:51], v[54:55], v[50:51]
	v_pk_add_f32 v[48:49], v[72:73], v[48:49]
	v_pk_add_f32 v[50:51], v[74:75], v[50:51]
	v_pk_add_f32 v[48:49], v[56:57], v[48:49]
	v_pk_add_f32 v[50:51], v[58:59], v[50:51]
	v_pk_add_f32 v[48:49], v[76:77], v[48:49]
	v_pk_add_f32 v[50:51], v[78:79], v[50:51]
	v_pk_add_f32 v[116:117], v[60:61], v[48:49]
	v_pk_add_f32 v[118:119], v[62:63], v[50:51]
	s_cmpk_gt_u32 s12, 61
	s_cselect_b64 s[44:45], -1, 0
	s_and_b64 vcc, exec, s[44:45]
	s_cbranch_vccnz .LBB0_846
	s_waitcnt vmcnt(0)
	ds_write_b128 v155, v[98:101]
	ds_write_b128 v156, v[106:109] offset:9216
	ds_write_b128 v155, v[236:239] offset:17408
	ds_write_b128 v156, v[240:243] offset:26624
	s_cmpk_gt_u32 s12, 58
	s_cbranch_scc1 .LBB0_846
	v_add_co_u32_e32 v48, vcc, 0xffc00000, v114
	s_nop 1
	v_addc_co_u32_e32 v49, vcc, -1, v115, vcc
	v_add_co_u32_e32 v50, vcc, 0xffc04000, v114
	s_nop 1
	v_addc_co_u32_e32 v51, vcc, -1, v115, vcc
	v_add_co_u32_e32 v52, vcc, 0x4000, v114
	s_nop 1
	v_addc_co_u32_e32 v53, vcc, 0, v115, vcc
	global_load_dwordx4 v[98:101], v[48:49], off
	global_load_dwordx4 v[106:109], v[114:115], off
	global_load_dwordx4 v[236:239], v[50:51], off
	global_load_dwordx4 v[240:243], v[52:53], off
	s_branch .LBB0_846
